# v3: + Q loads hoisted to unit start, attention outputs stored as dwordx4 via permlane32 swaps
# speedup vs baseline: 1.0073x; 1.0073x over previous
; __device__ __forceinline__ unsigned pk2(float lo, float hi) { f32x2 v = {lo, hi}; bf16x2_t b = __builtin_convertvector(v, bf16x2_t); return __builtin_bit_cast(unsigned, b); }
; __device__ __forceinline__ void attn_unit_c(LAS unsigned char* lds, const AU& u, int tid, int wid, int lane) {
;     ...
;     {
;         const float inv = 1.f / l;
;         bf16_t* op = u.O + (size_t)qidx * u.opitch + 4 * h;
; #pragma unroll
;         for (int g = 0; g < 4; ++g) {
;             u32x2 w0, w1;
;             w0.x = pk2(o0[4 * g] * inv, o0[4 * g + 1] * inv); w0.y = pk2(o0[4 * g + 2] * inv, o0[4 * g + 3] * inv);
;             w1.x = pk2(o1[4 * g] * inv, o1[4 * g + 1] * inv); w1.y = pk2(o1[4 * g + 2] * inv, o1[4 * g + 3] * inv);
;             *(u32x2*)(op + 8 * g) = w0; *(u32x2*)(op + 32 + 8 * g) = w1;
;         }
;     }
.LBB0_799:
	s_lshl_b64 s[0:1], s[30:31], 11
	s_add_u32 s0, s45, s0
	s_addc_u32 s1, s46, s1
	s_lshl_b32 s4, s75, 7
	s_add_u32 s0, s0, s4
	v_div_scale_f32 v32, s[4:5], v165, v165, 1.0
	v_rcp_f32_e32 v33, v32
	s_addc_u32 s1, s1, 0
	v_lshlrev_b32_e32 v112, 2, v172
	v_fma_f32 v34, -v32, v33, 1.0
	v_fmac_f32_e32 v33, v34, v33
	v_div_scale_f32 v34, vcc, 1.0, v165, 1.0
	v_mul_f32_e32 v35, v34, v33
	v_fma_f32 v36, -v32, v35, v34
	v_fmac_f32_e32 v35, v36, v33
	v_fma_f32 v32, -v32, v35, v34
	v_div_fmas_f32 v32, v32, v33, v35
	v_div_fixup_f32 v32, v32, v165, 1.0
	v_lshlrev_b64 v[34:35], 11, v[152:153]
	v_lshl_add_u64 v[34:35], s[0:1], 0, v[34:35]
	v_lshl_add_u64 v[34:35], v[34:35], 0, v[112:113]
	v_pk_mul_f32 v[0:1], v[0:1], v[32:33] op_sel_hi:[1,0]
	v_pk_mul_f32 v[2:3], v[2:3], v[32:33] op_sel_hi:[1,0]
	v_pk_mul_f32 v[4:5], v[4:5], v[32:33] op_sel_hi:[1,0]
	v_pk_mul_f32 v[6:7], v[6:7], v[32:33] op_sel_hi:[1,0]
	v_cvt_pk_bf16_f32 v0, v0, v1
	v_cvt_pk_bf16_f32 v1, v2, v3
	v_cvt_pk_bf16_f32 v2, v4, v5
	v_cvt_pk_bf16_f32 v3, v6, v7
	v_pk_mul_f32 v[8:9], v[8:9], v[32:33] op_sel_hi:[1,0]
	v_pk_mul_f32 v[10:11], v[10:11], v[32:33] op_sel_hi:[1,0]
	v_pk_mul_f32 v[12:13], v[12:13], v[32:33] op_sel_hi:[1,0]
	v_pk_mul_f32 v[14:15], v[14:15], v[32:33] op_sel_hi:[1,0]
	v_cvt_pk_bf16_f32 v8, v8, v9
	v_cvt_pk_bf16_f32 v9, v10, v11
	v_cvt_pk_bf16_f32 v10, v12, v13
	v_cvt_pk_bf16_f32 v11, v14, v15
	v_pk_mul_f32 v[16:17], v[16:17], v[32:33] op_sel_hi:[1,0]
	v_pk_mul_f32 v[18:19], v[18:19], v[32:33] op_sel_hi:[1,0]
	v_pk_mul_f32 v[20:21], v[20:21], v[32:33] op_sel_hi:[1,0]
	v_pk_mul_f32 v[22:23], v[22:23], v[32:33] op_sel_hi:[1,0]
	v_cvt_pk_bf16_f32 v16, v16, v17
	v_cvt_pk_bf16_f32 v17, v18, v19
	v_cvt_pk_bf16_f32 v18, v20, v21
	v_cvt_pk_bf16_f32 v19, v22, v23
	v_pk_mul_f32 v[24:25], v[24:25], v[32:33] op_sel_hi:[1,0]
	v_pk_mul_f32 v[26:27], v[26:27], v[32:33] op_sel_hi:[1,0]
	v_pk_mul_f32 v[28:29], v[28:29], v[32:33] op_sel_hi:[1,0]
	v_pk_mul_f32 v[30:31], v[30:31], v[32:33] op_sel_hi:[1,0]
	v_cvt_pk_bf16_f32 v24, v24, v25
	v_cvt_pk_bf16_f32 v25, v26, v27
	v_cvt_pk_bf16_f32 v26, v28, v29
	v_cvt_pk_bf16_f32 v27, v30, v31
	s_nop 1
	v_permlane32_swap_b32_e32 v0, v2
	v_permlane32_swap_b32_e32 v1, v3
	v_permlane32_swap_b32_e32 v8, v10
	v_permlane32_swap_b32_e32 v9, v11
	v_permlane32_swap_b32_e32 v16, v18
	v_permlane32_swap_b32_e32 v17, v19
	v_permlane32_swap_b32_e32 v24, v26
	v_permlane32_swap_b32_e32 v25, v27
	global_store_dwordx4 v[34:35], v[0:3], off offset:1024
	global_store_dwordx4 v[34:35], v[8:11], off offset:1056
	global_store_dwordx4 v[34:35], v[16:19], off offset:1088
	global_store_dwordx4 v[34:35], v[24:27], off offset:1120
	s_barrier

; #define LAS __attribute__((address_space(3)))
; __device__ __forceinline__ void attn_unit_w(LAS unsigned char* lds, const AU& u, int tid, int wid, int lane) {
;     ...
;     bf16x8 qf[4];
;     { const bf16_t* qp = u.Q + (size_t)qidx * u.qpitch + 8 * h;
; #pragma unroll
;       for (int ks = 0; ks < 4; ++ks) qf[ks] = *(const bf16x8*)(qp + 16 * ks); }
;     float m = u.m0, l = u.l0;
;     f32x16 o0, o1;
; #pragma unroll
;     for (int i = 0; i < 16; ++i) { o0[i] = 0.f; o1[i] = 0.f; }
;     const int qlo = u.q0 + 32 * wid;
;     int t_lo = (qlo - u.R) >> 6, t_hi = ((qlo + 31 + u.R) >> 6) + 1;
;     t_lo = t_lo < u.kt_lo ? u.kt_lo : t_lo; t_hi = t_hi > u.kt_hi ? u.kt_hi : t_hi;
;     LAS unsigned char* Vw = lds + wid * BW_VBYTES;
;     const int vkey = lane >> 3, vch = lane & 7;
;     bf16x8 kf[8]; u32x4 vr[8];
;     const bf16_t* kbase = u.K1 + (size_t)r * u.k1pitch + 8 * h;
;     const bf16_t* vbase = u.V + (size_t)vkey * u.vpitch + 8 * vch;
;     ...
;     __syncthreads();
;     if (t_lo < t_hi) BW_LOAD(t_lo);
.LBB0_807:
	s_lshl_b32 s98, s0, 8
	s_add_i32 s99, s98, s65
	v_or_b32_e32 v214, s99, v173
	v_ashrrev_i32_e32 v215, 31, v214
	v_lshlrev_b64 v[214:215], 7, v[214:215]
	v_lshl_add_u64 v[214:215], s[28:29], 0, v[214:215]
	v_lshlrev_b32_e32 v216, 1, v170
	v_mov_b32_e32 v217, 0
	v_lshl_add_u64 v[214:215], v[214:215], 0, v[216:217]
	global_load_dwordx4 v[64:67], v[214:215], off
	global_load_dwordx4 v[68:71], v[214:215], off offset:32
	global_load_dwordx4 v[72:75], v[214:215], off offset:64
	global_load_dwordx4 v[76:79], v[214:215], off offset:96
	s_lshl_b32 s98, s0, 8
	s_sub_i32 s99, s98, s62
	s_ashr_i32 s99, s99, 6
	s_max_i32 s99, s99, 0
	s_add_i32 s98, s98, s62
	s_addk_i32 s98, 0xc0
	s_lshr_b32 s98, s98, 6
	s_add_i32 s98, s98, 1
	s_min_u32 s98, s98, s63
	s_sub_i32 s98, s98, s99
	s_lshr_b32 s100, s65, 5
	s_cmp_lt_u32 s100, s98
	s_cbranch_scc0 .Lw3_noload
	s_add_i32 s99, s99, s100
	s_lshl_b32 s99, s99, 13
	s_lshl_b32 s100, s100, 13
	v_and_b32_e32 v214, 63, v171
	v_lshlrev_b32_e32 v216, 4, v214
	v_add_u32_e32 v216, s99, v216
	v_mov_b32_e32 v217, 0
	v_lshl_add_u64 v[216:217], s[4:5], 0, v[216:217]
	v_and_b32_e32 v218, 56, v214
	v_lshlrev_b32_e32 v218, 4, v218
	v_and_b32_e32 v219, 7, v214
	v_lshlrev_b32_e32 v219, 4, v219
	v_and_b32_e32 v214, 16, v214
	v_lshlrev_b32_e32 v214, 2, v214
	v_xor_b32_e32 v219, v219, v214
	v_add3_u32 v218, v218, v219, s99
	v_mov_b32_e32 v219, 0
	v_lshl_add_u64 v[218:219], s[26:27], 0, v[218:219]
	s_mov_b32 m0, s100
	s_nop 0
	global_load_lds_dwordx4 v[216:217], off
	global_load_lds_dwordx4 v[216:217], off offset:1024
	global_load_lds_dwordx4 v[216:217], off offset:2048
	global_load_lds_dwordx4 v[216:217], off offset:3072
	s_add_i32 m0, s100, 0x10000
	s_nop 0
	global_load_lds_dwordx4 v[218:219], off
	global_load_lds_dwordx4 v[218:219], off offset:1024
	global_load_lds_dwordx4 v[218:219], off offset:2048
	global_load_lds_dwordx4 v[218:219], off offset:3072
	v_add_co_u32_e32 v216, vcc, 0x1000, v216
	s_nop 1
	v_addc_co_u32_e32 v217, vcc, 0, v217, vcc
	v_add_co_u32_e32 v218, vcc, 0x1000, v218
	s_nop 1
	v_addc_co_u32_e32 v219, vcc, 0, v219, vcc
	s_add_i32 m0, s100, 0x1000
	s_nop 0
	global_load_lds_dwordx4 v[216:217], off
	global_load_lds_dwordx4 v[216:217], off offset:1024
	global_load_lds_dwordx4 v[216:217], off offset:2048
	global_load_lds_dwordx4 v[216:217], off offset:3072
	s_add_i32 m0, s100, 0x11000
	s_nop 0
	global_load_lds_dwordx4 v[218:219], off
	global_load_lds_dwordx4 v[218:219], off offset:1024
	global_load_lds_dwordx4 v[218:219], off offset:2048
	global_load_lds_dwordx4 v[218:219], off offset:3072

; #define LAS __attribute__((address_space(3)))
; __device__ __forceinline__ void attn_unit_w(LAS unsigned char* lds, const AU& u, int tid, int wid, int lane) {
;     ...
;     float m = u.m0, l = u.l0;
;     f32x16 o0, o1;
; #pragma unroll
;     for (int i = 0; i < 16; ++i) { o0[i] = 0.f; o1[i] = 0.f; }
;     const int qlo = u.q0 + 32 * wid;
;     int t_lo = (qlo - u.R) >> 6, t_hi = ((qlo + 31 + u.R) >> 6) + 1;
;     t_lo = t_lo < u.kt_lo ? u.kt_lo : t_lo; t_hi = t_hi > u.kt_hi ? u.kt_hi : t_hi;
;     LAS unsigned char* Vw = lds + wid * BW_VBYTES;
;     const int vkey = lane >> 3, vch = lane & 7;
;     bf16x8 kf[8]; u32x4 vr[8];
;     const bf16_t* kbase = u.K1 + (size_t)r * u.k1pitch + 8 * h;
;     const bf16_t* vbase = u.V + (size_t)vkey * u.vpitch + 8 * vch;
;     ...
;     __syncthreads();
;     if (t_lo < t_hi) BW_LOAD(t_lo);
;     const int trow = 4 * h + ((lane & 15) >> 2), tcol = (16 * ((lane >> 4) & 1) + 4 * (lane & 3)) * 2;
;     for (int kt = t_lo; kt < t_hi; ++kt) {
; #pragma unroll
;         for (int j = 0; j < 8; ++j) *(LAS u32x4*)(Vw + (vkey + 8 * j) * BW_VP + 16 * vch) = vr[j];
;         bf16x8 kc[8];
; #pragma unroll
;         for (int i = 0; i < 8; ++i) kc[i] = kf[i];
;         if (kt + 1 < t_hi) BW_LOAD(kt + 1);
;         f32x16 p0, p1;
; #pragma unroll
;         for (int i = 0; i < 16; ++i) { p0[i] = 0.f; p1[i] = 0.f; }
.LBB0_812:
	s_or_b64 exec, exec, s[36:37]
	s_lshl_b32 s0, s0, 8
	s_add_i32 s12, s0, s65
	v_or_b32_e32 v0, s12, v173
	v_ashrrev_i32_e32 v1, 31, v0
	v_lshlrev_b64 v[0:1], 7, v[0:1]
	v_lshl_add_u64 v[0:1], s[28:29], 0, v[0:1]
	v_lshlrev_b32_e32 v112, 1, v170
	v_lshl_add_u64 v[0:1], v[0:1], 0, v[112:113]
	s_or_b32 s28, s62, s0
	s_addk_i32 s28, 0xc0
	s_lshr_b32 s28, s28, 6
	s_add_i32 s28, s28, 1
	s_min_u32 s29, s28, s63
	s_sub_i32 s28, s12, s62
	s_add_i32 s12, s12, s62
	s_sub_i32 s13, s0, s62
	s_ashr_i32 s12, s12, 6
	s_ashr_i32 s13, s13, 6
	s_ashr_i32 s28, s28, 6
	s_add_i32 s30, s12, 1
	v_mov_b32_e32 v0, s28
	s_cmp_lt_i32 s12, s29
	v_max3_i32 v0, s13, v0, 0
	s_cselect_b32 s29, s30, s29
	v_cmp_gt_i32_e32 vcc, s29, v0
	v_readfirstlane_b32 s28, v0
	v_mov_b32_e32 v15, 0
	s_mov_b32 s70, 0x16401000
	s_waitcnt vmcnt(0) lgkmcnt(0)
	s_barrier
	s_cbranch_vccz .LBB0_818
	v_add_lshl_u32 v40, v202, s0, 2
	s_lshl_b32 s4, s28, 8
	s_lshl_b32 s5, s62, 2
	s_add_i32 s4, s4, s5
	v_sub_u32_e32 v40, s4, v40
	v_add_u32_e32 v112, v207, v40
	s_max_i32 s98, s13, 0
	s_sub_i32 s98, s28, s98
	s_lshl_b32 s98, s98, 13
	v_add_u32_e32 v221, s98, v186
	v_and_b32_e32 v222, 63, v171
	v_lshrrev_b32_e32 v223, 2, v222
	v_and_b32_e32 v223, 3, v223
	v_lshrrev_b32_e32 v224, 5, v222
	v_lshl_or_b32 v223, v224, 2, v223
	v_and_b32_e32 v224, 8, v222
	v_lshlrev_b32_e32 v224, 3, v224
	v_xor_b32_e32 v224, v224, v200
	v_lshl_or_b32 v222, v223, 7, v224
	s_add_i32 s98, s98, 0x10000
	v_add_u32_e32 v222, s98, v222
	v_xor_b32_e32 v223, 64, v222
	ds_read_b128 v[114:117], v221
	ds_read_b128 v[118:121], v221 offset:1024
	ds_read_b128 v[126:129], v221 offset:4096
	ds_read_b128 v[130:133], v221 offset:5120
	ds_read_b128 v[122:125], v221 offset:2048
	ds_read_b128 v[134:137], v221 offset:3072
	ds_read_b128 v[138:141], v221 offset:6144
	ds_read_b128 v[142:145], v221 offset:7168
	v_readlane_b32 s62, v255, 34
	v_mov_b32_e32 v187, s59
	v_mov_b32_e32 v0, 0
	v_mov_b32_e32 v1, v0
	v_mov_b32_e32 v2, v0
	v_mov_b32_e32 v3, v0
	v_mov_b32_e32 v4, v0
	v_mov_b32_e32 v5, v0
	v_mov_b32_e32 v6, v0
	v_mov_b32_e32 v7, v0
	v_mov_b32_e32 v8, v0
	v_mov_b32_e32 v9, v0
	v_mov_b32_e32 v10, v0
	v_mov_b32_e32 v11, v0
	v_mov_b32_e32 v12, v0
	v_mov_b32_e32 v13, v0
	v_mov_b32_e32 v14, v0
	v_mov_b32_e32 v15, v0
	v_mov_b32_e32 v16, v0
	v_mov_b32_e32 v17, v0
	v_mov_b32_e32 v18, v0
	v_mov_b32_e32 v19, v0
	v_mov_b32_e32 v20, v0
	v_mov_b32_e32 v21, v0
	v_mov_b32_e32 v22, v0
	v_mov_b32_e32 v23, v0
	v_mov_b32_e32 v24, v0
	v_mov_b32_e32 v25, v0
	v_mov_b32_e32 v26, v0
	v_mov_b32_e32 v27, v0
	v_mov_b32_e32 v28, v0
	v_mov_b32_e32 v29, v0
	v_mov_b32_e32 v30, v0
	v_mov_b32_e32 v31, v0
	v_readlane_b32 s63, v255, 35

; __device__ __forceinline__ unsigned pk2(float lo, float hi) { f32x2 v = {lo, hi}; bf16x2_t b = __builtin_convertvector(v, bf16x2_t); return __builtin_bit_cast(unsigned, b); }
; __device__ __forceinline__ void attn_unit_w(LAS unsigned char* lds, const AU& u, int tid, int wid, int lane) {
;     ...
;     {
;         int qidx2 = u.q0 + 32 * wid + r; asm volatile("" : "+v"(qidx2));
;         const float inv = 1.f / l;
;         bf16_t* op = u.O + (size_t)qidx2 * u.opitch + 4 * h;
; #pragma unroll
;         for (int g = 0; g < 4; ++g) {
;             u32x2 w0, w1;
;             w0.x = pk2(o0[4 * g] * inv, o0[4 * g + 1] * inv); w0.y = pk2(o0[4 * g + 2] * inv, o0[4 * g + 3] * inv);
;             w1.x = pk2(o1[4 * g] * inv, o1[4 * g + 1] * inv); w1.y = pk2(o1[4 * g + 2] * inv, o1[4 * g + 3] * inv);
;             *(u32x2*)(op + 8 * g) = w0; *(u32x2*)(op + 32 + 8 * g) = w1;
;         }
;         if (u.LSE && h == 0) u.LSE[(size_t)qidx2 * u.lsepitch] = m + __builtin_amdgcn_logf(l);
;     }
.LBB0_819:
	v_div_scale_f32 v33, s[4:5], v40, v40, 1.0
	v_rcp_f32_e32 v34, v33
	v_add_u32_e32 v32, s0, v202
	v_lshlrev_b32_e32 v112, 2, v172
	v_fma_f32 v35, -v33, v34, 1.0
	v_fmac_f32_e32 v34, v35, v34
	v_div_scale_f32 v35, vcc, 1.0, v40, 1.0
	v_mul_f32_e32 v36, v35, v34
	v_fma_f32 v37, -v33, v36, v35
	v_fmac_f32_e32 v36, v37, v34
	v_fma_f32 v33, -v33, v36, v35
	v_div_fmas_f32 v33, v33, v34, v36
	v_div_fixup_f32 v34, v33, v40, 1.0
	v_ashrrev_i32_e32 v33, 31, v32
	v_mul_lo_u32 v35, s24, v33
	v_mul_lo_u32 v38, s25, v32
	v_mad_u64_u32 v[36:37], s[4:5], s24, v32, 0
	v_add3_u32 v37, v37, v35, v38
	v_lshl_add_u64 v[36:37], v[36:37], 1, s[20:21]
	v_lshl_add_u64 v[36:37], v[36:37], 0, v[112:113]
	v_pk_mul_f32 v[0:1], v[0:1], v[34:35] op_sel_hi:[1,0]
	v_pk_mul_f32 v[2:3], v[2:3], v[34:35] op_sel_hi:[1,0]
	v_pk_mul_f32 v[4:5], v[4:5], v[34:35] op_sel_hi:[1,0]
	v_pk_mul_f32 v[6:7], v[6:7], v[34:35] op_sel_hi:[1,0]
	v_cvt_pk_bf16_f32 v0, v0, v1
	v_cvt_pk_bf16_f32 v1, v2, v3
	v_cvt_pk_bf16_f32 v2, v4, v5
	v_cvt_pk_bf16_f32 v3, v6, v7
	v_pk_mul_f32 v[8:9], v[8:9], v[34:35] op_sel_hi:[1,0]
	v_pk_mul_f32 v[10:11], v[10:11], v[34:35] op_sel_hi:[1,0]
	v_pk_mul_f32 v[12:13], v[12:13], v[34:35] op_sel_hi:[1,0]
	v_pk_mul_f32 v[14:15], v[14:15], v[34:35] op_sel_hi:[1,0]
	v_cvt_pk_bf16_f32 v8, v8, v9
	v_cvt_pk_bf16_f32 v9, v10, v11
	v_cvt_pk_bf16_f32 v10, v12, v13
	v_cvt_pk_bf16_f32 v11, v14, v15
	v_pk_mul_f32 v[16:17], v[16:17], v[34:35] op_sel_hi:[1,0]
	v_pk_mul_f32 v[18:19], v[18:19], v[34:35] op_sel_hi:[1,0]
	v_pk_mul_f32 v[20:21], v[20:21], v[34:35] op_sel_hi:[1,0]
	v_pk_mul_f32 v[22:23], v[22:23], v[34:35] op_sel_hi:[1,0]
	v_cvt_pk_bf16_f32 v16, v16, v17
	v_cvt_pk_bf16_f32 v17, v18, v19
	v_cvt_pk_bf16_f32 v18, v20, v21
	v_cvt_pk_bf16_f32 v19, v22, v23
	v_pk_mul_f32 v[24:25], v[24:25], v[34:35] op_sel_hi:[1,0]
	v_pk_mul_f32 v[26:27], v[26:27], v[34:35] op_sel_hi:[1,0]
	v_pk_mul_f32 v[28:29], v[28:29], v[34:35] op_sel_hi:[1,0]
	v_pk_mul_f32 v[30:31], v[30:31], v[34:35] op_sel_hi:[1,0]
	v_cvt_pk_bf16_f32 v24, v24, v25
	v_cvt_pk_bf16_f32 v25, v26, v27
	v_cvt_pk_bf16_f32 v26, v28, v29
	v_cvt_pk_bf16_f32 v27, v30, v31
	s_nop 1
	v_permlane32_swap_b32_e32 v0, v2
	v_permlane32_swap_b32_e32 v1, v3
	v_permlane32_swap_b32_e32 v8, v10
	v_permlane32_swap_b32_e32 v9, v11
	v_permlane32_swap_b32_e32 v16, v18
	v_permlane32_swap_b32_e32 v17, v19
	v_permlane32_swap_b32_e32 v24, v26
	v_permlane32_swap_b32_e32 v25, v27
	global_store_dwordx4 v[36:37], v[0:3], off
	global_store_dwordx4 v[36:37], v[8:11], off offset:32
	global_store_dwordx4 v[36:37], v[16:19], off offset:64
	global_store_dwordx4 v[36:37], v[24:27], off offset:96
	s_cmp_lg_u64 s[6:7], 0
	s_cselect_b64 s[4:5], -1, 0
	s_mov_b32 s28, 0x2400000
	s_mov_b32 s29, 0x2401000
	s_and_b64 s[12:13], s[4:5], s[8:9]
	s_and_saveexec_b64 s[4:5], s[12:13]
	s_cbranch_execz .LBB0_821
	v_log_f32_e32 v0, v40
	v_mul_lo_u32 v2, s19, v32
	v_mul_lo_u32 v3, s18, v33
	v_add_f32_e32 v4, v50, v0
	v_mad_u64_u32 v[0:1], s[12:13], s18, v32, 0
	v_add3_u32 v1, v1, v3, v2
	v_lshl_add_u64 v[0:1], v[0:1], 2, s[6:7]
	global_store_dword v[0:1], v4, off
